# gMLP preamble: LayerNorm gain/bias load issued early and written to LDS right before the wave-unit loop (no vmcnt wait + barrier in the preamble; lgkmcnt wait kept; the statistics-exchange barrier pub
# speedup vs baseline: 1.0011x; 1.0011x over previous
.Lgd_pre:
	global_load_dwordx4 v[212:215], v[2:3], off
	v_readlane_b32 s0, v251, 18
	s_add_i32 s16, s83, s0
	v_and_b32_e32 v157, 31, v200
	s_waitcnt lgkmcnt(0)
	s_cmpk_gt_i32 s16, 0x7ff
	s_cbranch_scc1 .LBB0_126
	v_readlane_b32 s0, v255, 61
	s_nop 3
	s_bitcmp1_b32 s0, 0
	s_cbranch_scc1 .LBB0_126
	v_readlane_b32 s0, v252, 27
	v_lshrrev_b32_e32 v0, 5, v244
	v_readlane_b32 s0, v251, 23
	v_lshlrev_b32_e32 v1, 3, v0
	s_lshl_b64 s[0:1], s[94:95], 18
	v_readlane_b32 s2, v251, 21
	v_or_b32_e32 v3, 7, v1
	v_readlane_b32 s3, v251, 22
	s_add_u32 s0, s2, s0
	v_cmp_gt_u32_e64 s[84:85], v3, v157
	v_or_b32_e32 v3, 6, v1
	s_addc_u32 s1, s3, s1
	v_lshlrev_b32_e32 v192, 4, v0
	v_cmp_gt_u32_e64 s[86:87], v3, v157
	v_or_b32_e32 v3, 5, v1
	v_lshl_add_u64 v[158:159], s[0:1], 0, v[192:193]
	v_cmp_gt_u32_e64 s[0:1], v3, v157
	v_or_b32_e32 v3, 4, v1
	v_or_b32_e32 v2, 32, v244
	v_writelane_b32 v253, s0, 53
	v_readlane_b32 s4, v251, 4
	s_lshl_b64 s[2:3], s[94:95], 12
	v_writelane_b32 v253, s1, 54
	v_cmp_gt_u32_e64 s[0:1], v3, v157
	v_or_b32_e32 v3, 3, v1
	v_readlane_b32 s6, v251, 6
	v_writelane_b32 v253, s0, 55
	v_readlane_b32 s7, v251, 7
	s_add_u32 s12, s6, s2
	v_writelane_b32 v253, s1, 56
	v_cmp_gt_u32_e64 s[0:1], v3, v157
	v_or_b32_e32 v3, 2, v1
	s_mul_i32 s2, s83, 0x4400
	v_writelane_b32 v253, s0, 57
	s_addc_u32 s13, s7, s3
	s_add_i32 s2, s2, 0
	v_writelane_b32 v253, s1, 58
	v_cmp_gt_u32_e64 s[0:1], v3, v157
	v_or_b32_e32 v3, 23, v1
	v_add_u32_e32 v161, s2, v4
	v_writelane_b32 v253, s0, 59
	v_or_b32_e32 v4, 0x47, v1
	v_lshl_add_u32 v165, v0, 6, s2
	v_writelane_b32 v253, s1, 60
	v_cmp_lt_u32_e64 s[0:1], v1, v157
	v_and_b32_e32 v0, 7, v200
	v_add_u32_e32 v163, s2, v192
	v_writelane_b32 v253, s0, 61
	v_lshlrev_b32_e32 v167, 3, v0
	v_lshl_add_u32 v0, v0, 5, s2
	v_writelane_b32 v253, s1, 62
	v_cmp_gt_u32_e64 s[0:1], v3, v157
	v_or_b32_e32 v3, 22, v1
	s_lshl_b32 s14, s83, 6
	v_writelane_b32 v253, s0, 63
	v_readlane_b32 s5, v251, 5
	v_lshrrev_b32_e32 v160, 3, v244
	v_writelane_b32 v254, s1, 0
	v_cmp_gt_u32_e64 s[0:1], v3, v157
	v_or_b32_e32 v3, 21, v1
	v_readlane_b32 s8, v251, 8
	v_writelane_b32 v254, s0, 1
	v_readlane_b32 s9, v251, 9
	v_readlane_b32 s10, v251, 10
	v_writelane_b32 v254, s1, 2
	v_cmp_gt_u32_e64 s[0:1], v3, v157
	v_or_b32_e32 v3, 20, v1
	v_readlane_b32 s11, v251, 11
	v_writelane_b32 v254, s0, 3
	v_mul_u32_u24_e32 v171, 0x110, v2
	v_cmp_gt_u32_e64 s[52:53], v1, v157
	v_writelane_b32 v254, s1, 4
	v_cmp_gt_u32_e64 s[0:1], v3, v157
	v_or_b32_e32 v3, 19, v1
	v_readlane_b32 s36, v252, 13
	v_writelane_b32 v254, s0, 5
	v_readlane_b32 s80, v252, 17
	v_readlane_b32 s28, v252, 15
	v_writelane_b32 v254, s1, 6
	v_cmp_gt_u32_e64 s[0:1], v3, v157
	v_or_b32_e32 v3, 18, v1
	v_readlane_b32 s4, v252, 19
	v_writelane_b32 v254, s0, 7
	s_mov_b32 s27, s46
	v_lshlrev_b32_e32 v156, 1, v244
	v_writelane_b32 v254, s1, 8
	v_cmp_gt_u32_e64 s[0:1], v3, v157
	v_or_b32_e32 v3, 17, v1
	v_or_b32_e32 v162, 64, v160
	v_writelane_b32 v254, s0, 9
	v_mul_u32_u24_e32 v169, 0x110, v157
	v_or_b32_e32 v164, 8, v160
	v_writelane_b32 v254, s1, 10
	v_cmp_gt_u32_e64 s[0:1], v3, v157
	v_or_b32_e32 v3, 16, v1
	v_or_b32_e32 v166, 16, v160
	v_writelane_b32 v254, s0, 11
	v_or_b32_e32 v168, 24, v160
	v_or_b32_e32 v170, 32, v160
	v_writelane_b32 v254, s1, 12
	v_cmp_gt_u32_e64 s[0:1], v3, v157
	v_or_b32_e32 v3, 39, v1
	v_or_b32_e32 v172, 40, v160
	v_writelane_b32 v254, s0, 13
	v_or_b32_e32 v174, 48, v160
	v_or_b32_e32 v176, 56, v160
	v_writelane_b32 v254, s1, 14
	v_cmp_gt_u32_e64 s[0:1], v3, v2
	v_or_b32_e32 v3, 38, v1
	v_or_b32_e32 v178, 0x48, v160
	v_writelane_b32 v254, s0, 15
	v_or_b32_e32 v180, 0x50, v160
	v_or_b32_e32 v182, 0x58, v160
	v_writelane_b32 v254, s1, 16
	v_cmp_gt_u32_e64 s[0:1], v3, v2
	v_or_b32_e32 v3, 37, v1
	v_or_b32_e32 v184, 0x60, v160
	v_writelane_b32 v254, s0, 17
	v_or_b32_e32 v186, 0x68, v160
	v_or_b32_e32 v188, 0x70, v160
	v_writelane_b32 v254, s1, 18
	v_cmp_gt_u32_e64 s[0:1], v3, v2
	v_or_b32_e32 v3, 36, v1
	v_or_b32_e32 v190, 0x78, v160
	v_writelane_b32 v254, s0, 19
	v_readlane_b32 s37, v252, 14
	v_readlane_b32 s81, v252, 18
	v_writelane_b32 v254, s1, 20
	v_cmp_gt_u32_e64 s[0:1], v3, v2
	v_or_b32_e32 v3, 35, v1
	v_readlane_b32 s29, v252, 16
	v_writelane_b32 v254, s0, 21
	v_readlane_b32 s5, v252, 20
	v_readlane_b32 s23, v253, 12
	v_writelane_b32 v254, s1, 22
	v_cmp_gt_u32_e64 s[0:1], v3, v2
	v_or_b32_e32 v3, 34, v1
	s_movk_i32 s25, 0x4000
	v_writelane_b32 v254, s0, 23
	s_mov_b32 s44, 0x3a800000
	s_nop 0
	v_writelane_b32 v254, s1, 24
	v_cmp_gt_u32_e64 s[0:1], v3, v2
	v_or_b32_e32 v3, 33, v1
	s_nop 0
	v_writelane_b32 v254, s0, 25
	s_nop 1
	v_writelane_b32 v254, s1, 26
	v_cmp_gt_u32_e64 s[0:1], v3, v2
	v_or_b32_e32 v3, 32, v1
	s_nop 0
	v_writelane_b32 v254, s0, 27
	s_nop 1
	v_writelane_b32 v254, s1, 28
	v_cmp_gt_u32_e64 s[0:1], v3, v2
	v_or_b32_e32 v3, 55, v1
	s_nop 0
	v_writelane_b32 v254, s0, 29
	s_nop 1
	v_writelane_b32 v254, s1, 30
	v_cmp_gt_u32_e64 s[0:1], v3, v2
	v_or_b32_e32 v3, 54, v1
	s_nop 0
	v_writelane_b32 v254, s0, 31
	s_nop 1
	v_writelane_b32 v254, s1, 32
	v_cmp_gt_u32_e64 s[0:1], v3, v2
	v_or_b32_e32 v3, 53, v1
	s_nop 0
	v_writelane_b32 v254, s0, 33
	s_nop 1
	v_writelane_b32 v254, s1, 34
	v_cmp_gt_u32_e64 s[0:1], v3, v2
	v_or_b32_e32 v3, 52, v1
	s_nop 0
	v_writelane_b32 v254, s0, 35
	s_nop 1
	v_writelane_b32 v254, s1, 36
	v_cmp_gt_u32_e64 s[0:1], v3, v2
	v_or_b32_e32 v3, 51, v1
	s_nop 0
	v_writelane_b32 v254, s0, 37
	s_nop 1
	v_writelane_b32 v254, s1, 38
	v_cmp_gt_u32_e64 s[0:1], v3, v2
	v_or_b32_e32 v3, 50, v1
	s_nop 0
	v_writelane_b32 v254, s0, 39
	s_nop 1
	v_writelane_b32 v254, s1, 40
	v_cmp_gt_u32_e64 s[0:1], v3, v2
	v_or_b32_e32 v3, 49, v1
	s_nop 0
	v_writelane_b32 v254, s0, 41
	s_nop 1
	v_writelane_b32 v254, s1, 42
	v_cmp_gt_u32_e64 s[0:1], v3, v2
	v_or_b32_e32 v3, 48, v1
	s_nop 0
	v_writelane_b32 v254, s0, 43
	s_nop 1
	v_writelane_b32 v254, s1, 44
	v_cmp_gt_u32_e64 s[0:1], v3, v2
	v_or_b32_e32 v3, 64, v157
	v_mul_u32_u24_e32 v2, 0x110, v160
	v_writelane_b32 v254, s0, 45
	v_add_u32_e32 v173, v0, v2
	s_nop 0
	v_writelane_b32 v254, s1, 46
	v_cmp_gt_u32_e64 s[0:1], v4, v3
	v_or_b32_e32 v4, 0x46, v1
	s_nop 0
	v_writelane_b32 v254, s0, 47
	s_nop 1
	v_writelane_b32 v254, s1, 48
	v_cmp_gt_u32_e64 s[0:1], v4, v3
	v_or_b32_e32 v4, 0x45, v1
	s_nop 0
	v_writelane_b32 v254, s0, 49
	s_nop 1
	v_writelane_b32 v254, s1, 50
	v_cmp_gt_u32_e64 s[0:1], v4, v3
	v_or_b32_e32 v4, 0x44, v1
	s_nop 0
	v_writelane_b32 v254, s0, 51
	s_nop 1
	v_writelane_b32 v254, s1, 52
	v_cmp_gt_u32_e64 s[0:1], v4, v3
	v_or_b32_e32 v4, 0x43, v1
	s_nop 0
	v_writelane_b32 v254, s0, 53
	s_nop 1
	v_writelane_b32 v254, s1, 54
	v_cmp_gt_u32_e64 s[0:1], v4, v3
	v_or_b32_e32 v4, 0x42, v1
	s_nop 0
	v_writelane_b32 v254, s0, 55
	s_nop 1
	v_writelane_b32 v254, s1, 56
	v_cmp_gt_u32_e64 s[0:1], v4, v3
	v_or_b32_e32 v4, 0x41, v1
	s_nop 0
	v_writelane_b32 v254, s0, 57
	s_nop 1
	v_writelane_b32 v254, s1, 58
	v_cmp_gt_u32_e64 s[0:1], v4, v3
	v_or_b32_e32 v4, 0x57, v1
	s_nop 0
	v_writelane_b32 v254, s0, 59
	s_nop 1
	v_writelane_b32 v254, s1, 60
	v_cmp_gt_u32_e64 s[0:1], v4, v3
	v_or_b32_e32 v4, 0x56, v1
	s_nop 0
	v_writelane_b32 v254, s0, 61
	s_nop 1
	v_writelane_b32 v254, s1, 62
	v_cmp_gt_u32_e64 s[0:1], v4, v3
	v_or_b32_e32 v4, 0x55, v1
	s_nop 0
	v_writelane_b32 v254, s0, 63
	s_nop 1
	v_writelane_b32 v255, s1, 0
	v_cmp_gt_u32_e64 s[0:1], v4, v3
	v_or_b32_e32 v4, 0x54, v1
	s_nop 0
	v_writelane_b32 v255, s0, 1
	s_nop 1
	v_writelane_b32 v255, s1, 2
	v_cmp_gt_u32_e64 s[0:1], v4, v3
	v_or_b32_e32 v4, 0x53, v1
	s_nop 0
	v_writelane_b32 v255, s0, 3
	s_nop 1
	v_writelane_b32 v255, s1, 4
	v_cmp_gt_u32_e64 s[0:1], v4, v3
	v_or_b32_e32 v4, 0x52, v1
	s_nop 0
	v_writelane_b32 v255, s0, 5
	s_nop 1
	v_writelane_b32 v255, s1, 6
	v_cmp_gt_u32_e64 s[0:1], v4, v3
	v_or_b32_e32 v4, 0x51, v1
	s_nop 0
	v_writelane_b32 v255, s0, 7
	s_nop 1
	v_writelane_b32 v255, s1, 8
	v_cmp_gt_u32_e64 s[0:1], v4, v3
	v_or_b32_e32 v4, 0x50, v1
	s_nop 0
	v_writelane_b32 v255, s0, 9
	s_nop 1
	v_writelane_b32 v255, s1, 10
	v_cmp_gt_u32_e64 s[0:1], v4, v3
	v_or_b32_e32 v3, 0x60, v244
	v_or_b32_e32 v4, 0x67, v1
	v_writelane_b32 v255, s0, 11
	s_nop 1
	v_writelane_b32 v255, s1, 12
	v_cmp_gt_u32_e64 s[0:1], v4, v3
	v_or_b32_e32 v4, 0x66, v1
	s_nop 0
	v_writelane_b32 v255, s0, 13
	s_nop 1
	v_writelane_b32 v255, s1, 14
	v_cmp_gt_u32_e64 s[0:1], v4, v3
	v_or_b32_e32 v4, 0x65, v1
	s_nop 0
	v_writelane_b32 v255, s0, 15
	s_nop 1
	v_writelane_b32 v255, s1, 16
	v_cmp_gt_u32_e64 s[0:1], v4, v3
	v_or_b32_e32 v4, 0x64, v1
	s_nop 0
	v_writelane_b32 v255, s0, 17
	s_nop 1
	v_writelane_b32 v255, s1, 18
	v_cmp_gt_u32_e64 s[0:1], v4, v3
	v_or_b32_e32 v4, 0x63, v1
	s_nop 0
	v_writelane_b32 v255, s0, 19
	s_nop 1
	v_writelane_b32 v255, s1, 20
	v_cmp_gt_u32_e64 s[0:1], v4, v3
	v_or_b32_e32 v4, 0x62, v1
	s_nop 0
	v_writelane_b32 v255, s0, 21
	s_nop 1
	v_writelane_b32 v255, s1, 22
	v_cmp_gt_u32_e64 s[0:1], v4, v3
	v_or_b32_e32 v4, 0x61, v1
	s_nop 0
	v_writelane_b32 v255, s0, 23
	s_nop 1
	v_writelane_b32 v255, s1, 24
	v_cmp_gt_u32_e64 s[0:1], v4, v3
	v_or_b32_e32 v4, 0x60, v1
	s_nop 0
	v_writelane_b32 v255, s0, 25
	s_nop 1
	v_writelane_b32 v255, s1, 26
	v_cmp_gt_u32_e64 s[0:1], v4, v3
	v_or_b32_e32 v4, 0x77, v1
	s_nop 0
	v_writelane_b32 v255, s0, 27
	s_nop 1
	v_writelane_b32 v255, s1, 28
	v_cmp_gt_u32_e64 s[0:1], v4, v3
	v_or_b32_e32 v4, 0x76, v1
	s_nop 0
	v_writelane_b32 v255, s0, 29
	s_nop 1
	v_writelane_b32 v255, s1, 30
	v_cmp_gt_u32_e64 s[0:1], v4, v3
	v_or_b32_e32 v4, 0x75, v1
	s_nop 0
	v_writelane_b32 v255, s0, 31
	s_nop 1
	v_writelane_b32 v255, s1, 32
	v_cmp_gt_u32_e64 s[0:1], v4, v3
	v_or_b32_e32 v4, 0x74, v1
	v_cmp_gt_u32_e64 s[2:3], v4, v3
	v_writelane_b32 v255, s0, 33
	v_or_b32_e32 v4, 0x73, v1
	v_cmp_gt_u32_e64 s[40:41], v4, v3
	v_writelane_b32 v255, s1, 34
	v_readlane_b32 s0, v253, 10
	v_or_b32_e32 v4, 0x72, v1
	s_add_i32 s17, s0, s14
	s_lshl_b32 s14, s83, 3
	v_readlane_b32 s0, v253, 11
	v_cmp_gt_u32_e64 s[6:7], v4, v3
	v_or_b32_e32 v4, 0x71, v1
	v_or_b32_e32 v1, 0x70, v1
	s_add_i32 s18, s0, s14
	v_readlane_b32 s14, v253, 39
	v_readlane_b32 s0, v252, 21
	v_cmp_gt_u32_e64 s[8:9], v4, v3
	v_cmp_gt_u32_e64 s[10:11], v1, v3
	s_mov_b32 s26, s14
	v_readlane_b32 s1, v252, 22
	v_readlane_b32 s15, v253, 40
	v_lshlrev_b32_e32 v216, 4, v200
	v_add_u32_e32 v216, 0x22000, v216
	s_waitcnt vmcnt(0)
	ds_write_b128 v216, v[212:215]
